# P2 K-loop: B-tile LDS-DMA loads nt
# baseline (speedup 1.0000x reference)
; #define PG8_STAGE(bufoff, gbase, voff) do { _Pragma("unroll") for (int _i = 0; _i < 2; ++_i) \
;         __builtin_amdgcn_global_load_lds((const unsigned*)((const char*)(gbase) + (voff)[_i]), (PG8_LAS unsigned*)(lds + (bufoff) + ldsw + _i * 8192), 16, 0, 0); } while (0)
; #define PG8_LDA(dst, b, h) do { _Pragma("unroll") for (int m = 0; m < 4; ++m) _Pragma("unroll") for (int k = 0; k < 2; ++k) dst[m][k] = *(const PG8_LAS bf16x8*)(lds + PG8_SA(b, h) + aoff + m * 2048 + k * 1024); } while (0)
; #define PG8_LDB(dst, b, h) do { _Pragma("unroll") for (int n = 0; n < 2; ++n) _Pragma("unroll") for (int k = 0; k < 2; ++k) dst[n][k] = *(const PG8_LAS bf16x8*)(lds + PG8_SB(b, h) + boff + n * 2048 + k * 1024); } while (0)
; #define PG8_MMA(ai, bj, At, Bt) do { __builtin_amdgcn_s_setprio(1); _Pragma("unroll") for (int m = 0; m < 4; ++m) _Pragma("unroll") for (int n = 0; n < 2; ++n) _Pragma("unroll") for (int k = 0; k < 2; ++k) \
;         acc[ai][bj][m][n] = __builtin_amdgcn_mfma_f32_16x16x32_bf16(Bt[n][k], At[m][k], acc[ai][bj][m][n], 0, 0, 0); __builtin_amdgcn_s_setprio(0); } while (0)
; #define PG8_WAIT_V(n) asm volatile("s_waitcnt vmcnt(" #n ")" ::: "memory")
; #define PG8_WAIT_L(n) asm volatile("s_waitcnt lgkmcnt(" #n ")" ::: "memory")
; #define PG8_BAR __builtin_amdgcn_s_barrier()
; #define PG8_SCHED __builtin_amdgcn_sched_barrier(0)
; template <class Epi, class Sched, bool ALIGN_EPI = false, bool SP2 = false>
; __device__ __forceinline__ void gemm_phase(PG8_LAS unsigned char* lds, const Gemm g, const Sched& S, const Epi& E) {
;     ...
;             PG8_LDB(B0, 0, 0); PG8_LDB(B1, 0, 1); PG8_SCHED; PG8_LDA(At, 0, 0); PG8_STAGE(PG8_SA(1, 1), a1 + hstepA, voffA);
;             PG8_WAIT_V(8); PG8_WAIT_L(0); PG8_BAR; PG8_MMA(0, 0, At, B0); PG8_MMA(0, 1, At, B1); PG8_BAR; PG8_SCHED;
;             PG8_LDA(At, 0, 1); PG8_STAGE(PG8_SB(0, 0), b2, voffB); PG8_STAGE(PG8_SB(0, 1), b2 + hstepB, voffB); PG8_STAGE(PG8_SA(0, 0), a2, voffA);
;             PG8_WAIT_V(8); PG8_WAIT_L(0); PG8_BAR; PG8_MMA(1, 0, At, B0); PG8_MMA(1, 1, At, B1); PG8_BAR; PG8_SCHED;
.LBB0_197:
	s_waitcnt lgkmcnt(0)
	ds_read_b128 v[146:149], v159
	ds_read_b128 v[162:165], v159 offset:1024
	ds_read_b128 v[166:169], v159 offset:2048
	ds_read_b128 v[170:173], v159 offset:3072
	ds_read_b128 v[176:179], v160
	ds_read_b128 v[180:183], v160 offset:1024
	ds_read_b128 v[184:187], v160 offset:2048
	ds_read_b128 v[188:191], v160 offset:3072
	s_add_u32 s66, s60, 0xfffc0080
	s_addc_u32 s67, s61, -1
	s_cmp_eq_u32 s74, 12
	s_cselect_b32 s85, s15, s67
	s_cselect_b32 s84, vcc_lo, s66
	s_cselect_b32 s67, s13, s81
	s_cselect_b32 s66, vcc_hi, s80
	v_lshl_add_u64 v[224:225], s[60:61], 0, v[138:139]
	s_add_i32 m0, s59, 0xc000
	ds_read_b128 v[192:195], v161
	ds_read_b128 v[196:199], v161 offset:1024
	ds_read_b128 v[200:203], v161 offset:2048
	ds_read_b128 v[204:207], v161 offset:3072
	ds_read_b128 v[208:211], v161 offset:4096
	ds_read_b128 v[212:215], v161 offset:5120
	ds_read_b128 v[216:219], v161 offset:6144
	ds_read_b128 v[220:223], v161 offset:7168
	global_load_lds_dwordx4 v[224:225], off
	v_lshl_add_u64 v[224:225], s[60:61], 0, v[140:141]
	s_add_i32 m0, s59, 0xe000
	s_nop 0
	global_load_lds_dwordx4 v[224:225], off
	s_waitcnt vmcnt(8)
	s_waitcnt lgkmcnt(0)
	s_barrier
	s_setprio 1
	s_waitcnt lgkmcnt(0)
	v_mfma_f32_16x16x32_bf16 v[124:127], v[146:149], v[192:195], v[124:127]
	v_mfma_f32_16x16x32_bf16 v[120:123], v[166:169], v[192:195], v[120:123]
	v_mfma_f32_16x16x32_bf16 v[116:119], v[146:149], v[200:203], v[116:119]
	v_mfma_f32_16x16x32_bf16 v[112:115], v[166:169], v[200:203], v[112:115]
	v_mfma_f32_16x16x32_bf16 v[108:111], v[146:149], v[208:211], v[108:111]
	v_mfma_f32_16x16x32_bf16 v[104:107], v[166:169], v[208:211], v[104:107]
	v_mfma_f32_16x16x32_bf16 v[100:103], v[146:149], v[216:219], v[100:103]
	v_mfma_f32_16x16x32_bf16 v[96:99], v[166:169], v[216:219], v[96:99]
	v_mfma_f32_16x16x32_bf16 v[124:127], v[162:165], v[196:199], v[124:127]
	v_mfma_f32_16x16x32_bf16 v[120:123], v[170:173], v[196:199], v[120:123]
	v_mfma_f32_16x16x32_bf16 v[116:119], v[162:165], v[204:207], v[116:119]
	v_mfma_f32_16x16x32_bf16 v[112:115], v[170:173], v[204:207], v[112:115]
	v_mfma_f32_16x16x32_bf16 v[108:111], v[162:165], v[212:215], v[108:111]
	v_mfma_f32_16x16x32_bf16 v[104:107], v[170:173], v[212:215], v[104:107]
	v_mfma_f32_16x16x32_bf16 v[100:103], v[162:165], v[220:223], v[100:103]
	v_mfma_f32_16x16x32_bf16 v[96:99], v[170:173], v[220:223], v[96:99]
	s_setprio 0
	s_setprio 1
	v_mfma_f32_16x16x32_bf16 v[68:71], v[176:179], v[192:195], v[68:71]
	v_mfma_f32_16x16x32_bf16 v[64:67], v[184:187], v[192:195], v[64:67]
	v_mfma_f32_16x16x32_bf16 v[56:59], v[176:179], v[200:203], v[56:59]
	v_mfma_f32_16x16x32_bf16 v[48:51], v[184:187], v[200:203], v[48:51]
	v_mfma_f32_16x16x32_bf16 v[44:47], v[176:179], v[208:211], v[44:47]
	v_mfma_f32_16x16x32_bf16 v[40:43], v[184:187], v[208:211], v[40:43]
	v_mfma_f32_16x16x32_bf16 v[36:39], v[176:179], v[216:219], v[36:39]
	v_mfma_f32_16x16x32_bf16 v[32:35], v[184:187], v[216:219], v[32:35]
	v_mfma_f32_16x16x32_bf16 v[68:71], v[180:183], v[196:199], v[68:71]
	v_mfma_f32_16x16x32_bf16 v[64:67], v[188:191], v[196:199], v[64:67]
	v_mfma_f32_16x16x32_bf16 v[56:59], v[180:183], v[204:207], v[56:59]
	v_mfma_f32_16x16x32_bf16 v[48:51], v[188:191], v[204:207], v[48:51]
	v_mfma_f32_16x16x32_bf16 v[44:47], v[180:183], v[212:215], v[44:47]
	v_mfma_f32_16x16x32_bf16 v[40:43], v[188:191], v[212:215], v[40:43]
	v_mfma_f32_16x16x32_bf16 v[36:39], v[180:183], v[220:223], v[36:39]
	v_mfma_f32_16x16x32_bf16 v[32:35], v[188:191], v[220:223], v[32:35]
	s_setprio 0
	s_barrier
	s_add_i32 s75, s38, s27
	v_lshl_add_u64 v[224:225], s[66:67], 0, v[132:133]
	s_mov_b32 m0, s75
	ds_read_b128 v[192:195], v161 offset:16384
	ds_read_b128 v[196:199], v161 offset:17408
	ds_read_b128 v[200:203], v161 offset:18432
	ds_read_b128 v[204:207], v161 offset:19456
	ds_read_b128 v[208:211], v161 offset:20480
	ds_read_b128 v[212:215], v161 offset:21504
	ds_read_b128 v[216:219], v161 offset:22528
	ds_read_b128 v[220:223], v161 offset:23552
	global_load_lds_dwordx4 v[224:225], off nt
	s_add_i32 m0, s75, 0x2000
	s_add_u32 s76, s66, 0x40000
	v_lshl_add_u64 v[226:227], s[66:67], 0, v[128:129]
	s_addc_u32 s77, s67, 0
	s_add_i32 s75, s39, s27
	global_load_lds_dwordx4 v[226:227], off nt
	v_lshl_add_u64 v[228:229], s[76:77], 0, v[132:133]
	s_mov_b32 m0, s75
	v_lshl_add_u64 v[230:231], s[84:85], 0, v[130:131]
	global_load_lds_dwordx4 v[228:229], off nt
	v_lshl_add_u64 v[228:229], s[76:77], 0, v[128:129]
	s_add_i32 m0, s75, 0x2000
	s_nop 0
	global_load_lds_dwordx4 v[228:229], off nt
	v_lshl_add_u64 v[228:229], s[84:85], 0, v[134:135]
	s_mov_b32 m0, s59
	s_nop 0
	global_load_lds_dwordx4 v[228:229], off
	s_mov_b32 m0, s86
	s_nop 0
	global_load_lds_dwordx4 v[230:231], off
	s_waitcnt vmcnt(8)
	s_waitcnt lgkmcnt(0)
	s_barrier
; #define PG8_STAGE(bufoff, gbase, voff) do { _Pragma("unroll") for (int _i = 0; _i < 2; ++_i) \
;         __builtin_amdgcn_global_load_lds((const unsigned*)((const char*)(gbase) + (voff)[_i]), (PG8_LAS unsigned*)(lds + (bufoff) + ldsw + _i * 8192), 16, 0, 0); } while (0)
; #define PG8_LDA(dst, b, h) do { _Pragma("unroll") for (int m = 0; m < 4; ++m) _Pragma("unroll") for (int k = 0; k < 2; ++k) dst[m][k] = *(const PG8_LAS bf16x8*)(lds + PG8_SA(b, h) + aoff + m * 2048 + k * 1024); } while (0)
; #define PG8_LDB(dst, b, h) do { _Pragma("unroll") for (int n = 0; n < 2; ++n) _Pragma("unroll") for (int k = 0; k < 2; ++k) dst[n][k] = *(const PG8_LAS bf16x8*)(lds + PG8_SB(b, h) + boff + n * 2048 + k * 1024); } while (0)
; #define PG8_MMA(ai, bj, At, Bt) do { __builtin_amdgcn_s_setprio(1); _Pragma("unroll") for (int m = 0; m < 4; ++m) _Pragma("unroll") for (int n = 0; n < 2; ++n) _Pragma("unroll") for (int k = 0; k < 2; ++k) \
;         acc[ai][bj][m][n] = __builtin_amdgcn_mfma_f32_16x16x32_bf16(Bt[n][k], At[m][k], acc[ai][bj][m][n], 0, 0, 0); __builtin_amdgcn_s_setprio(0); } while (0)
; #define PG8_WAIT_V(n) asm volatile("s_waitcnt vmcnt(" #n ")" ::: "memory")
; #define PG8_WAIT_L(n) asm volatile("s_waitcnt lgkmcnt(" #n ")" ::: "memory")
; #define PG8_BAR __builtin_amdgcn_s_barrier()
; #define PG8_SCHED __builtin_amdgcn_sched_barrier(0)
; template <class Epi, class Sched, bool ALIGN_EPI = false, bool SP2 = false>
; __device__ __forceinline__ void gemm_phase(PG8_LAS unsigned char* lds, const Gemm g, const Sched& S, const Epi& E) {
;     ...
;             PG8_WAIT_V(8); PG8_WAIT_L(0); PG8_BAR; PG8_MMA(1, 0, At, B0); PG8_MMA(1, 1, At, B1); PG8_BAR; PG8_SCHED;
;             PG8_LDB(B0, 1, 0); PG8_LDB(B1, 1, 1); PG8_SCHED; PG8_LDA(At, 1, 0); PG8_STAGE(PG8_SA(0, 1), a2 + hstepA, voffA);
;             PG8_WAIT_V(8); PG8_WAIT_L(0); PG8_BAR; PG8_MMA(0, 0, At, B0); PG8_MMA(0, 1, At, B1); PG8_BAR; PG8_SCHED;
	s_setprio 1
	s_waitcnt lgkmcnt(0)
	v_mfma_f32_16x16x32_bf16 v[92:95], v[146:149], v[192:195], v[92:95]
	v_mfma_f32_16x16x32_bf16 v[88:91], v[166:169], v[192:195], v[88:91]
	v_mfma_f32_16x16x32_bf16 v[84:87], v[146:149], v[200:203], v[84:87]
	v_mfma_f32_16x16x32_bf16 v[80:83], v[166:169], v[200:203], v[80:83]
	v_mfma_f32_16x16x32_bf16 v[76:79], v[146:149], v[208:211], v[76:79]
	v_mfma_f32_16x16x32_bf16 v[72:75], v[166:169], v[208:211], v[72:75]
	v_mfma_f32_16x16x32_bf16 v[60:63], v[146:149], v[216:219], v[60:63]
	v_mfma_f32_16x16x32_bf16 v[52:55], v[166:169], v[216:219], v[52:55]
	v_mfma_f32_16x16x32_bf16 v[92:95], v[162:165], v[196:199], v[92:95]
	v_mfma_f32_16x16x32_bf16 v[88:91], v[170:173], v[196:199], v[88:91]
	v_mfma_f32_16x16x32_bf16 v[84:87], v[162:165], v[204:207], v[84:87]
	v_mfma_f32_16x16x32_bf16 v[80:83], v[170:173], v[204:207], v[80:83]
	v_mfma_f32_16x16x32_bf16 v[76:79], v[162:165], v[212:215], v[76:79]
	v_mfma_f32_16x16x32_bf16 v[72:75], v[170:173], v[212:215], v[72:75]
	v_mfma_f32_16x16x32_bf16 v[60:63], v[162:165], v[220:223], v[60:63]
	v_mfma_f32_16x16x32_bf16 v[52:55], v[170:173], v[220:223], v[52:55]
	s_setprio 0
	s_setprio 1
	v_mfma_f32_16x16x32_bf16 v[28:31], v[176:179], v[192:195], v[28:31]
	v_mfma_f32_16x16x32_bf16 v[24:27], v[184:187], v[192:195], v[24:27]
	v_mfma_f32_16x16x32_bf16 v[20:23], v[176:179], v[200:203], v[20:23]
	v_mfma_f32_16x16x32_bf16 v[16:19], v[184:187], v[200:203], v[16:19]
	v_mfma_f32_16x16x32_bf16 v[12:15], v[176:179], v[208:211], v[12:15]
	v_mfma_f32_16x16x32_bf16 v[8:11], v[184:187], v[208:211], v[8:11]
	v_mfma_f32_16x16x32_bf16 v[4:7], v[176:179], v[216:219], v[4:7]
	v_mfma_f32_16x16x32_bf16 v[0:3], v[184:187], v[216:219], v[0:3]
	v_mfma_f32_16x16x32_bf16 v[28:31], v[180:183], v[196:199], v[28:31]
	v_mfma_f32_16x16x32_bf16 v[24:27], v[188:191], v[196:199], v[24:27]
	v_mfma_f32_16x16x32_bf16 v[20:23], v[180:183], v[204:207], v[20:23]
	v_mfma_f32_16x16x32_bf16 v[16:19], v[188:191], v[204:207], v[16:19]
	v_mfma_f32_16x16x32_bf16 v[12:15], v[180:183], v[212:215], v[12:15]
	v_mfma_f32_16x16x32_bf16 v[8:11], v[188:191], v[212:215], v[8:11]
	v_mfma_f32_16x16x32_bf16 v[4:7], v[180:183], v[220:223], v[4:7]
	v_mfma_f32_16x16x32_bf16 v[0:3], v[188:191], v[220:223], v[0:3]
	s_setprio 0
	s_barrier
	s_add_i32 s75, 0, 0x18000
	s_add_i32 s33, 0, 0x1c000
	v_add_u32_e32 v170, s75, v151
	v_add_u32_e32 v175, s33, v151
	ds_read_b128 v[146:149], v170
	ds_read_b128 v[162:165], v170 offset:1024
	ds_read_b128 v[166:169], v170 offset:2048
	ds_read_b128 v[170:173], v170 offset:3072
	ds_read_b128 v[176:179], v175
	ds_read_b128 v[180:183], v175 offset:1024
	ds_read_b128 v[184:187], v175 offset:2048
	ds_read_b128 v[188:191], v175 offset:3072
	s_add_u32 s76, s84, 0x40000
	s_addc_u32 s77, s85, 0
	s_mov_b32 m0, s87
	v_lshl_add_u64 v[232:233], s[76:77], 0, v[134:135]
	ds_read_b128 v[192:195], v161 offset:32768
	ds_read_b128 v[196:199], v161 offset:33792
	ds_read_b128 v[200:203], v161 offset:34816
	ds_read_b128 v[204:207], v161 offset:35840
	ds_read_b128 v[208:211], v161 offset:36864
	ds_read_b128 v[212:215], v161 offset:37888
	ds_read_b128 v[216:219], v161 offset:38912
	ds_read_b128 v[220:223], v161 offset:39936
	global_load_lds_dwordx4 v[232:233], off
	v_lshl_add_u64 v[232:233], s[76:77], 0, v[130:131]
	s_mov_b32 m0, s88
	s_nop 0
	global_load_lds_dwordx4 v[232:233], off
	s_waitcnt vmcnt(8)
	s_waitcnt lgkmcnt(0)
	s_barrier
	s_setprio 1
	s_waitcnt lgkmcnt(0)
	v_mfma_f32_16x16x32_bf16 v[124:127], v[146:149], v[192:195], v[124:127]
	v_mfma_f32_16x16x32_bf16 v[120:123], v[166:169], v[192:195], v[120:123]
	v_mfma_f32_16x16x32_bf16 v[116:119], v[146:149], v[200:203], v[116:119]
	v_mfma_f32_16x16x32_bf16 v[112:115], v[166:169], v[200:203], v[112:115]
	v_mfma_f32_16x16x32_bf16 v[108:111], v[146:149], v[208:211], v[108:111]
	v_mfma_f32_16x16x32_bf16 v[104:107], v[166:169], v[208:211], v[104:107]
	v_mfma_f32_16x16x32_bf16 v[100:103], v[146:149], v[216:219], v[100:103]
	v_mfma_f32_16x16x32_bf16 v[96:99], v[166:169], v[216:219], v[96:99]
	v_mfma_f32_16x16x32_bf16 v[124:127], v[162:165], v[196:199], v[124:127]
	v_mfma_f32_16x16x32_bf16 v[120:123], v[170:173], v[196:199], v[120:123]
	v_mfma_f32_16x16x32_bf16 v[116:119], v[162:165], v[204:207], v[116:119]
	v_mfma_f32_16x16x32_bf16 v[112:115], v[170:173], v[204:207], v[112:115]
	v_mfma_f32_16x16x32_bf16 v[108:111], v[162:165], v[212:215], v[108:111]
	v_mfma_f32_16x16x32_bf16 v[104:107], v[170:173], v[212:215], v[104:107]
	v_mfma_f32_16x16x32_bf16 v[100:103], v[162:165], v[220:223], v[100:103]
	v_mfma_f32_16x16x32_bf16 v[96:99], v[170:173], v[220:223], v[96:99]
	s_setprio 0
	s_setprio 1
	v_mfma_f32_16x16x32_bf16 v[68:71], v[176:179], v[192:195], v[68:71]
	v_mfma_f32_16x16x32_bf16 v[64:67], v[184:187], v[192:195], v[64:67]
	v_mfma_f32_16x16x32_bf16 v[56:59], v[176:179], v[200:203], v[56:59]
	v_mfma_f32_16x16x32_bf16 v[48:51], v[184:187], v[200:203], v[48:51]
	v_mfma_f32_16x16x32_bf16 v[44:47], v[176:179], v[208:211], v[44:47]
	v_mfma_f32_16x16x32_bf16 v[40:43], v[184:187], v[208:211], v[40:43]
	v_mfma_f32_16x16x32_bf16 v[36:39], v[176:179], v[216:219], v[36:39]
	v_mfma_f32_16x16x32_bf16 v[32:35], v[184:187], v[216:219], v[32:35]
	v_mfma_f32_16x16x32_bf16 v[68:71], v[180:183], v[196:199], v[68:71]
	v_mfma_f32_16x16x32_bf16 v[64:67], v[188:191], v[196:199], v[64:67]
	v_mfma_f32_16x16x32_bf16 v[56:59], v[180:183], v[204:207], v[56:59]
	v_mfma_f32_16x16x32_bf16 v[48:51], v[188:191], v[204:207], v[48:51]
	v_mfma_f32_16x16x32_bf16 v[44:47], v[180:183], v[212:215], v[44:47]
	v_mfma_f32_16x16x32_bf16 v[40:43], v[188:191], v[212:215], v[40:43]
	v_mfma_f32_16x16x32_bf16 v[36:39], v[180:183], v[220:223], v[36:39]
	v_mfma_f32_16x16x32_bf16 v[32:35], v[188:191], v[220:223], v[32:35]
	s_setprio 0
	s_barrier
; #define PG8_STAGE(bufoff, gbase, voff) do { _Pragma("unroll") for (int _i = 0; _i < 2; ++_i) \
;         __builtin_amdgcn_global_load_lds((const unsigned*)((const char*)(gbase) + (voff)[_i]), (PG8_LAS unsigned*)(lds + (bufoff) + ldsw + _i * 8192), 16, 0, 0); } while (0)
; #define PG8_LDA(dst, b, h) do { _Pragma("unroll") for (int m = 0; m < 4; ++m) _Pragma("unroll") for (int k = 0; k < 2; ++k) dst[m][k] = *(const PG8_LAS bf16x8*)(lds + PG8_SA(b, h) + aoff + m * 2048 + k * 1024); } while (0)
; #define PG8_MMA(ai, bj, At, Bt) do { __builtin_amdgcn_s_setprio(1); _Pragma("unroll") for (int m = 0; m < 4; ++m) _Pragma("unroll") for (int n = 0; n < 2; ++n) _Pragma("unroll") for (int k = 0; k < 2; ++k) \
;         acc[ai][bj][m][n] = __builtin_amdgcn_mfma_f32_16x16x32_bf16(Bt[n][k], At[m][k], acc[ai][bj][m][n], 0, 0, 0); __builtin_amdgcn_s_setprio(0); } while (0)
; #define PG8_WAIT_V(n) asm volatile("s_waitcnt vmcnt(" #n ")" ::: "memory")
; #define PG8_WAIT_L(n) asm volatile("s_waitcnt lgkmcnt(" #n ")" ::: "memory")
; #define PG8_BAR __builtin_amdgcn_s_barrier()
; #define PG8_SCHED __builtin_amdgcn_sched_barrier(0)
; template <class Epi, class Sched, bool ALIGN_EPI = false, bool SP2 = false>
; __device__ __forceinline__ void gemm_phase(PG8_LAS unsigned char* lds, const Gemm g, const Sched& S, const Epi& E) {
;     ...
;         for (int t = 0; t < nt; t += 2) {
;             const bool last = (t == nt - 2);
;             const char* a1 = cA + (size_t)(t + 1) * kstep;
;             const char* a2 = last ? nA : cA + (size_t)(t + 2) * kstep; const char* b2 = last ? nB : cB + (size_t)(t + 2) * kstep;
;     ...
;             PG8_LDA(At, 1, 1); PG8_STAGE(PG8_SB(1, 0), b3, voffB); PG8_STAGE(PG8_SB(1, 1), b3 + hstepB, voffB); PG8_STAGE(PG8_SA(1, 0), a3, voffA);
;             PG8_WAIT_V(8); PG8_WAIT_L(0); PG8_BAR; PG8_MMA(1, 0, At, B0); PG8_MMA(1, 1, At, B1); PG8_BAR; PG8_SCHED;
	s_add_i32 s75, s75, s27
	v_lshl_add_u64 v[224:225], v[224:225], 0, s[8:9]
	s_mov_b32 m0, s75
	ds_read_b128 v[192:195], v161 offset:49152
	ds_read_b128 v[196:199], v161 offset:50176
	ds_read_b128 v[200:203], v161 offset:51200
	ds_read_b128 v[204:207], v161 offset:52224
	ds_read_b128 v[208:211], v161 offset:53248
	ds_read_b128 v[212:215], v161 offset:54272
	ds_read_b128 v[216:219], v161 offset:55296
	ds_read_b128 v[220:223], v161 offset:56320
	global_load_lds_dwordx4 v[224:225], off nt
	s_add_i32 m0, s75, 0x2000
	s_add_u32 s66, s66, 0x40080
	v_lshl_add_u64 v[224:225], v[226:227], 0, s[8:9]
	s_addc_u32 s67, s67, 0
	s_add_i32 s33, s33, s27
	global_load_lds_dwordx4 v[224:225], off nt
	v_lshl_add_u64 v[224:225], s[66:67], 0, v[132:133]
	s_mov_b32 m0, s33
	s_nop 0
	global_load_lds_dwordx4 v[224:225], off nt
	v_lshl_add_u64 v[224:225], s[66:67], 0, v[128:129]
	s_add_i32 m0, s33, 0x2000
	s_nop 0
	global_load_lds_dwordx4 v[224:225], off nt
	v_lshl_add_u64 v[224:225], v[228:229], 0, s[8:9]
	s_mov_b32 m0, s91
	s_nop 0
	global_load_lds_dwordx4 v[224:225], off
	v_lshl_add_u64 v[224:225], v[230:231], 0, s[8:9]
	s_mov_b32 m0, s92
	s_nop 0
	global_load_lds_dwordx4 v[224:225], off
	s_waitcnt vmcnt(8)
	s_waitcnt lgkmcnt(0)
	s_barrier
	s_setprio 1
	s_waitcnt lgkmcnt(0)
	v_mfma_f32_16x16x32_bf16 v[92:95], v[146:149], v[192:195], v[92:95]
	v_mfma_f32_16x16x32_bf16 v[88:91], v[166:169], v[192:195], v[88:91]
	v_mfma_f32_16x16x32_bf16 v[84:87], v[146:149], v[200:203], v[84:87]
	v_mfma_f32_16x16x32_bf16 v[80:83], v[166:169], v[200:203], v[80:83]
	v_mfma_f32_16x16x32_bf16 v[76:79], v[146:149], v[208:211], v[76:79]
	v_mfma_f32_16x16x32_bf16 v[72:75], v[166:169], v[208:211], v[72:75]
	v_mfma_f32_16x16x32_bf16 v[60:63], v[146:149], v[216:219], v[60:63]
	v_mfma_f32_16x16x32_bf16 v[52:55], v[166:169], v[216:219], v[52:55]
	v_mfma_f32_16x16x32_bf16 v[92:95], v[162:165], v[196:199], v[92:95]
	v_mfma_f32_16x16x32_bf16 v[88:91], v[170:173], v[196:199], v[88:91]
	v_mfma_f32_16x16x32_bf16 v[84:87], v[162:165], v[204:207], v[84:87]
	v_mfma_f32_16x16x32_bf16 v[80:83], v[170:173], v[204:207], v[80:83]
	v_mfma_f32_16x16x32_bf16 v[76:79], v[162:165], v[212:215], v[76:79]
	v_mfma_f32_16x16x32_bf16 v[72:75], v[170:173], v[212:215], v[72:75]
	v_mfma_f32_16x16x32_bf16 v[60:63], v[162:165], v[220:223], v[60:63]
	v_mfma_f32_16x16x32_bf16 v[52:55], v[170:173], v[220:223], v[52:55]
	s_setprio 0
	s_setprio 1
	v_mfma_f32_16x16x32_bf16 v[28:31], v[176:179], v[192:195], v[28:31]
	v_mfma_f32_16x16x32_bf16 v[24:27], v[184:187], v[192:195], v[24:27]
	v_mfma_f32_16x16x32_bf16 v[20:23], v[176:179], v[200:203], v[20:23]
	v_mfma_f32_16x16x32_bf16 v[16:19], v[184:187], v[200:203], v[16:19]
	v_mfma_f32_16x16x32_bf16 v[12:15], v[176:179], v[208:211], v[12:15]
	v_mfma_f32_16x16x32_bf16 v[8:11], v[184:187], v[208:211], v[8:11]
	v_mfma_f32_16x16x32_bf16 v[4:7], v[176:179], v[216:219], v[4:7]
	v_mfma_f32_16x16x32_bf16 v[0:3], v[184:187], v[216:219], v[0:3]
	v_mfma_f32_16x16x32_bf16 v[28:31], v[180:183], v[196:199], v[28:31]
	v_mfma_f32_16x16x32_bf16 v[24:27], v[188:191], v[196:199], v[24:27]
	v_mfma_f32_16x16x32_bf16 v[20:23], v[180:183], v[204:207], v[20:23]
	v_mfma_f32_16x16x32_bf16 v[16:19], v[188:191], v[204:207], v[16:19]
	v_mfma_f32_16x16x32_bf16 v[12:15], v[180:183], v[212:215], v[12:15]
	v_mfma_f32_16x16x32_bf16 v[8:11], v[188:191], v[212:215], v[8:11]
	v_mfma_f32_16x16x32_bf16 v[4:7], v[180:183], v[220:223], v[4:7]
	v_mfma_f32_16x16x32_bf16 v[0:3], v[188:191], v[220:223], v[0:3]
	s_setprio 0
	s_barrier
	s_add_i32 s74, s74, 2
	s_add_u32 s60, s60, 0x100
	s_addc_u32 s61, s61, 0
	s_add_u32 s80, s80, 0x100
	s_addc_u32 s81, s81, 0
	s_cmp_gt_u32 s74, 13
	s_cbranch_scc0 .LBB0_197
	s_add_u32 s100, vcc_lo, 0x40080
	s_addc_u32 s101, s15, 0
	s_and_b64 vcc, exec, s[10:11]
	s_cbranch_vccnz .LBB0_203
	v_lshl_add_u64 v[224:225], s[100:101], 0, v[138:139]
	s_add_i32 m0, s59, 0xc000
	v_lshl_add_u64 v[226:227], s[100:101], 0, v[140:141]
	global_load_lds_dwordx4 v[224:225], off
	s_add_i32 m0, s59, 0xe000
	s_nop 0
	global_load_lds_dwordx4 v[226:227], off
	s_and_b32 s13, s73, -4
	s_cmp_lg_u32 s13, 4
	s_cbranch_scc0 .LBB0_204

; #define PG8_STAGE(bufoff, gbase, voff) do { _Pragma("unroll") for (int _i = 0; _i < 2; ++_i) \
;         __builtin_amdgcn_global_load_lds((const unsigned*)((const char*)(gbase) + (voff)[_i]), (PG8_LAS unsigned*)(lds + (bufoff) + ldsw + _i * 8192), 16, 0, 0); } while (0)
; #define PG8_LDA(dst, b, h) do { _Pragma("unroll") for (int m = 0; m < 4; ++m) _Pragma("unroll") for (int k = 0; k < 2; ++k) dst[m][k] = *(const PG8_LAS bf16x8*)(lds + PG8_SA(b, h) + aoff + m * 2048 + k * 1024); } while (0)
; #define PG8_LDB(dst, b, h) do { _Pragma("unroll") for (int n = 0; n < 2; ++n) _Pragma("unroll") for (int k = 0; k < 2; ++k) dst[n][k] = *(const PG8_LAS bf16x8*)(lds + PG8_SB(b, h) + boff + n * 2048 + k * 1024); } while (0)
; #define PG8_MMA(ai, bj, At, Bt) do { __builtin_amdgcn_s_setprio(1); _Pragma("unroll") for (int m = 0; m < 4; ++m) _Pragma("unroll") for (int n = 0; n < 2; ++n) _Pragma("unroll") for (int k = 0; k < 2; ++k) \
;         acc[ai][bj][m][n] = __builtin_amdgcn_mfma_f32_16x16x32_bf16(Bt[n][k], At[m][k], acc[ai][bj][m][n], 0, 0, 0); __builtin_amdgcn_s_setprio(0); } while (0)
; #define PG8_WAIT_V(n) asm volatile("s_waitcnt vmcnt(" #n ")" ::: "memory")
; #define PG8_WAIT_L(n) asm volatile("s_waitcnt lgkmcnt(" #n ")" ::: "memory")
; #define PG8_BAR __builtin_amdgcn_s_barrier()
; #define PG8_SCHED __builtin_amdgcn_sched_barrier(0)
; template <class Epi, class Sched, bool ALIGN_EPI = false, bool SP2 = false>
; __device__ __forceinline__ void gemm_phase(PG8_LAS unsigned char* lds, const Gemm g, const Sched& S, const Epi& E) {
;     ...
;             PG8_LDB(B0, 0, 0); PG8_LDB(B1, 0, 1); PG8_SCHED; PG8_LDA(At, 0, 0); PG8_STAGE(PG8_SA(1, 1), a1 + hstepA, voffA);
;             PG8_WAIT_V(8); PG8_WAIT_L(0); PG8_BAR; PG8_MMA(0, 0, At, B0); PG8_MMA(0, 1, At, B1); PG8_BAR; PG8_SCHED;
;             PG8_LDA(At, 0, 1); PG8_STAGE(PG8_SB(0, 0), b2, voffB); PG8_STAGE(PG8_SB(0, 1), b2 + hstepB, voffB); PG8_STAGE(PG8_SA(0, 0), a2, voffA);
;             PG8_WAIT_V(8); PG8_WAIT_L(0); PG8_BAR; PG8_MMA(1, 0, At, B0); PG8_MMA(1, 1, At, B1); PG8_BAR; PG8_SCHED;
.Lpeel_p2:
	s_waitcnt lgkmcnt(0)
	ds_read_b128 v[146:149], v159
	ds_read_b128 v[162:165], v159 offset:1024
	ds_read_b128 v[166:169], v159 offset:2048
	ds_read_b128 v[170:173], v159 offset:3072
	ds_read_b128 v[176:179], v160
	ds_read_b128 v[180:183], v160 offset:1024
	ds_read_b128 v[184:187], v160 offset:2048
	ds_read_b128 v[188:191], v160 offset:3072
	s_add_u32 s66, s60, 0xfffc0080
	s_addc_u32 s67, s61, -1
	s_cmp_eq_u32 s74, 12
	s_cselect_b32 s85, s15, s67
	s_cselect_b32 s84, vcc_lo, s66
	s_cselect_b32 s67, s13, s81
	s_cselect_b32 s66, vcc_hi, s80
	ds_read_b128 v[192:195], v161
	ds_read_b128 v[196:199], v161 offset:1024
	ds_read_b128 v[200:203], v161 offset:2048
	ds_read_b128 v[204:207], v161 offset:3072
	ds_read_b128 v[208:211], v161 offset:4096
	ds_read_b128 v[212:215], v161 offset:5120
	ds_read_b128 v[216:219], v161 offset:6144
	ds_read_b128 v[220:223], v161 offset:7168
	s_waitcnt vmcnt(24)
	s_waitcnt lgkmcnt(0)
	s_barrier
	s_setprio 1
	s_waitcnt lgkmcnt(0)
	v_mfma_f32_16x16x32_bf16 v[124:127], v[146:149], v[192:195], 0
	v_mfma_f32_16x16x32_bf16 v[120:123], v[166:169], v[192:195], 0
	v_mfma_f32_16x16x32_bf16 v[116:119], v[146:149], v[200:203], 0
	v_mfma_f32_16x16x32_bf16 v[112:115], v[166:169], v[200:203], 0
	v_mfma_f32_16x16x32_bf16 v[108:111], v[146:149], v[208:211], 0
	v_mfma_f32_16x16x32_bf16 v[104:107], v[166:169], v[208:211], 0
	v_mfma_f32_16x16x32_bf16 v[100:103], v[146:149], v[216:219], 0
	v_mfma_f32_16x16x32_bf16 v[96:99], v[166:169], v[216:219], 0
	v_mfma_f32_16x16x32_bf16 v[124:127], v[162:165], v[196:199], v[124:127]
	v_mfma_f32_16x16x32_bf16 v[120:123], v[170:173], v[196:199], v[120:123]
	v_mfma_f32_16x16x32_bf16 v[116:119], v[162:165], v[204:207], v[116:119]
	v_mfma_f32_16x16x32_bf16 v[112:115], v[170:173], v[204:207], v[112:115]
	v_mfma_f32_16x16x32_bf16 v[108:111], v[162:165], v[212:215], v[108:111]
	v_mfma_f32_16x16x32_bf16 v[104:107], v[170:173], v[212:215], v[104:107]
	v_mfma_f32_16x16x32_bf16 v[100:103], v[162:165], v[220:223], v[100:103]
	v_mfma_f32_16x16x32_bf16 v[96:99], v[170:173], v[220:223], v[96:99]
	s_setprio 0
	s_setprio 1
	v_mfma_f32_16x16x32_bf16 v[68:71], v[176:179], v[192:195], 0
	v_mfma_f32_16x16x32_bf16 v[64:67], v[184:187], v[192:195], 0
	v_mfma_f32_16x16x32_bf16 v[56:59], v[176:179], v[200:203], 0
	v_mfma_f32_16x16x32_bf16 v[48:51], v[184:187], v[200:203], 0
	v_mfma_f32_16x16x32_bf16 v[44:47], v[176:179], v[208:211], 0
	v_mfma_f32_16x16x32_bf16 v[40:43], v[184:187], v[208:211], 0
	v_mfma_f32_16x16x32_bf16 v[36:39], v[176:179], v[216:219], 0
	v_mfma_f32_16x16x32_bf16 v[32:35], v[184:187], v[216:219], 0
	v_mfma_f32_16x16x32_bf16 v[68:71], v[180:183], v[196:199], v[68:71]
	v_mfma_f32_16x16x32_bf16 v[64:67], v[188:191], v[196:199], v[64:67]
	v_mfma_f32_16x16x32_bf16 v[56:59], v[180:183], v[204:207], v[56:59]
	v_mfma_f32_16x16x32_bf16 v[48:51], v[188:191], v[204:207], v[48:51]
	v_mfma_f32_16x16x32_bf16 v[44:47], v[180:183], v[212:215], v[44:47]
	v_mfma_f32_16x16x32_bf16 v[40:43], v[188:191], v[212:215], v[40:43]
	v_mfma_f32_16x16x32_bf16 v[36:39], v[180:183], v[220:223], v[36:39]
	v_mfma_f32_16x16x32_bf16 v[32:35], v[188:191], v[220:223], v[32:35]
	s_setprio 0
	s_barrier
	s_add_i32 s75, s38, s27
	v_lshl_add_u64 v[224:225], s[66:67], 0, v[132:133]
	s_mov_b32 m0, s75
	ds_read_b128 v[192:195], v161 offset:16384
	ds_read_b128 v[196:199], v161 offset:17408
	ds_read_b128 v[200:203], v161 offset:18432
	ds_read_b128 v[204:207], v161 offset:19456
	ds_read_b128 v[208:211], v161 offset:20480
	ds_read_b128 v[212:215], v161 offset:21504
	ds_read_b128 v[216:219], v161 offset:22528
	ds_read_b128 v[220:223], v161 offset:23552
	global_load_lds_dwordx4 v[224:225], off nt
	s_add_i32 m0, s75, 0x2000
	s_add_u32 s76, s66, 0x40000
	v_lshl_add_u64 v[226:227], s[66:67], 0, v[128:129]
	s_addc_u32 s77, s67, 0
	s_add_i32 s75, s39, s27
	global_load_lds_dwordx4 v[226:227], off nt
	v_lshl_add_u64 v[228:229], s[76:77], 0, v[132:133]
	s_mov_b32 m0, s75
	v_lshl_add_u64 v[230:231], s[84:85], 0, v[130:131]
	global_load_lds_dwordx4 v[228:229], off nt
	v_lshl_add_u64 v[228:229], s[76:77], 0, v[128:129]
	s_add_i32 m0, s75, 0x2000
	s_nop 0
	global_load_lds_dwordx4 v[228:229], off nt
	v_lshl_add_u64 v[228:229], s[84:85], 0, v[134:135]
	s_mov_b32 m0, s59
	s_nop 0
	global_load_lds_dwordx4 v[228:229], off
	s_mov_b32 m0, s86
	s_nop 0
	global_load_lds_dwordx4 v[230:231], off
	s_waitcnt vmcnt(24)
	s_waitcnt lgkmcnt(0)
	s_barrier
	s_setprio 1
	s_waitcnt lgkmcnt(0)
	v_mfma_f32_16x16x32_bf16 v[92:95], v[146:149], v[192:195], 0
	v_mfma_f32_16x16x32_bf16 v[88:91], v[166:169], v[192:195], 0
	v_mfma_f32_16x16x32_bf16 v[84:87], v[146:149], v[200:203], 0
	v_mfma_f32_16x16x32_bf16 v[80:83], v[166:169], v[200:203], 0
	v_mfma_f32_16x16x32_bf16 v[76:79], v[146:149], v[208:211], 0
	v_mfma_f32_16x16x32_bf16 v[72:75], v[166:169], v[208:211], 0
	v_mfma_f32_16x16x32_bf16 v[60:63], v[146:149], v[216:219], 0
	v_mfma_f32_16x16x32_bf16 v[52:55], v[166:169], v[216:219], 0
	v_mfma_f32_16x16x32_bf16 v[92:95], v[162:165], v[196:199], v[92:95]
	v_mfma_f32_16x16x32_bf16 v[88:91], v[170:173], v[196:199], v[88:91]
	v_mfma_f32_16x16x32_bf16 v[84:87], v[162:165], v[204:207], v[84:87]
	v_mfma_f32_16x16x32_bf16 v[80:83], v[170:173], v[204:207], v[80:83]
	v_mfma_f32_16x16x32_bf16 v[76:79], v[162:165], v[212:215], v[76:79]
	v_mfma_f32_16x16x32_bf16 v[72:75], v[170:173], v[212:215], v[72:75]
	v_mfma_f32_16x16x32_bf16 v[60:63], v[162:165], v[220:223], v[60:63]
	v_mfma_f32_16x16x32_bf16 v[52:55], v[170:173], v[220:223], v[52:55]
	s_setprio 0
	s_setprio 1
	v_mfma_f32_16x16x32_bf16 v[28:31], v[176:179], v[192:195], 0
	v_mfma_f32_16x16x32_bf16 v[24:27], v[184:187], v[192:195], 0
	v_mfma_f32_16x16x32_bf16 v[20:23], v[176:179], v[200:203], 0
	v_mfma_f32_16x16x32_bf16 v[16:19], v[184:187], v[200:203], 0
	v_mfma_f32_16x16x32_bf16 v[12:15], v[176:179], v[208:211], 0
	v_mfma_f32_16x16x32_bf16 v[8:11], v[184:187], v[208:211], 0
	v_mfma_f32_16x16x32_bf16 v[4:7], v[176:179], v[216:219], 0
	v_mfma_f32_16x16x32_bf16 v[0:3], v[184:187], v[216:219], 0
	v_mfma_f32_16x16x32_bf16 v[28:31], v[180:183], v[196:199], v[28:31]
	v_mfma_f32_16x16x32_bf16 v[24:27], v[188:191], v[196:199], v[24:27]
	v_mfma_f32_16x16x32_bf16 v[20:23], v[180:183], v[204:207], v[20:23]
	v_mfma_f32_16x16x32_bf16 v[16:19], v[188:191], v[204:207], v[16:19]
	v_mfma_f32_16x16x32_bf16 v[12:15], v[180:183], v[212:215], v[12:15]
	v_mfma_f32_16x16x32_bf16 v[8:11], v[188:191], v[212:215], v[8:11]
	v_mfma_f32_16x16x32_bf16 v[4:7], v[180:183], v[220:223], v[4:7]
	v_mfma_f32_16x16x32_bf16 v[0:3], v[188:191], v[220:223], v[0:3]
	s_setprio 0
	s_barrier
; #define PG8_STAGE(bufoff, gbase, voff) do { _Pragma("unroll") for (int _i = 0; _i < 2; ++_i) \
;         __builtin_amdgcn_global_load_lds((const unsigned*)((const char*)(gbase) + (voff)[_i]), (PG8_LAS unsigned*)(lds + (bufoff) + ldsw + _i * 8192), 16, 0, 0); } while (0)
; #define PG8_LDA(dst, b, h) do { _Pragma("unroll") for (int m = 0; m < 4; ++m) _Pragma("unroll") for (int k = 0; k < 2; ++k) dst[m][k] = *(const PG8_LAS bf16x8*)(lds + PG8_SA(b, h) + aoff + m * 2048 + k * 1024); } while (0)
; #define PG8_LDB(dst, b, h) do { _Pragma("unroll") for (int n = 0; n < 2; ++n) _Pragma("unroll") for (int k = 0; k < 2; ++k) dst[n][k] = *(const PG8_LAS bf16x8*)(lds + PG8_SB(b, h) + boff + n * 2048 + k * 1024); } while (0)
; #define PG8_MMA(ai, bj, At, Bt) do { __builtin_amdgcn_s_setprio(1); _Pragma("unroll") for (int m = 0; m < 4; ++m) _Pragma("unroll") for (int n = 0; n < 2; ++n) _Pragma("unroll") for (int k = 0; k < 2; ++k) \
;         acc[ai][bj][m][n] = __builtin_amdgcn_mfma_f32_16x16x32_bf16(Bt[n][k], At[m][k], acc[ai][bj][m][n], 0, 0, 0); __builtin_amdgcn_s_setprio(0); } while (0)
; #define PG8_WAIT_V(n) asm volatile("s_waitcnt vmcnt(" #n ")" ::: "memory")
; #define PG8_WAIT_L(n) asm volatile("s_waitcnt lgkmcnt(" #n ")" ::: "memory")
; #define PG8_BAR __builtin_amdgcn_s_barrier()
; #define PG8_SCHED __builtin_amdgcn_sched_barrier(0)
; template <class Epi, class Sched, bool ALIGN_EPI = false, bool SP2 = false>
; __device__ __forceinline__ void gemm_phase(PG8_LAS unsigned char* lds, const Gemm g, const Sched& S, const Epi& E) {
;     ...
;             PG8_LDB(B0, 1, 0); PG8_LDB(B1, 1, 1); PG8_SCHED; PG8_LDA(At, 1, 0); PG8_STAGE(PG8_SA(0, 1), a2 + hstepA, voffA);
;             PG8_WAIT_V(8); PG8_WAIT_L(0); PG8_BAR; PG8_MMA(0, 0, At, B0); PG8_MMA(0, 1, At, B1); PG8_BAR; PG8_SCHED;
	s_add_i32 s75, 0, 0x18000
	s_add_i32 s33, 0, 0x1c000
	v_add_u32_e32 v170, s75, v151
	v_add_u32_e32 v175, s33, v151
	ds_read_b128 v[146:149], v170
	ds_read_b128 v[162:165], v170 offset:1024
	ds_read_b128 v[166:169], v170 offset:2048
	ds_read_b128 v[170:173], v170 offset:3072
	ds_read_b128 v[176:179], v175
	ds_read_b128 v[180:183], v175 offset:1024
	ds_read_b128 v[184:187], v175 offset:2048
	ds_read_b128 v[188:191], v175 offset:3072
	s_add_u32 s76, s84, 0x40000
	s_addc_u32 s77, s85, 0
	s_mov_b32 m0, s87
	v_lshl_add_u64 v[232:233], s[76:77], 0, v[134:135]
	ds_read_b128 v[192:195], v161 offset:32768
	ds_read_b128 v[196:199], v161 offset:33792
	ds_read_b128 v[200:203], v161 offset:34816
	ds_read_b128 v[204:207], v161 offset:35840
	ds_read_b128 v[208:211], v161 offset:36864
	ds_read_b128 v[212:215], v161 offset:37888
	ds_read_b128 v[216:219], v161 offset:38912
	ds_read_b128 v[220:223], v161 offset:39936
	global_load_lds_dwordx4 v[232:233], off
	v_lshl_add_u64 v[232:233], s[76:77], 0, v[130:131]
	s_mov_b32 m0, s88
	s_nop 0
	global_load_lds_dwordx4 v[232:233], off
	s_waitcnt vmcnt(24)
	s_waitcnt lgkmcnt(0)
	s_barrier
	s_setprio 1
	s_waitcnt lgkmcnt(0)
	v_mfma_f32_16x16x32_bf16 v[124:127], v[146:149], v[192:195], v[124:127]
	v_mfma_f32_16x16x32_bf16 v[120:123], v[166:169], v[192:195], v[120:123]
	v_mfma_f32_16x16x32_bf16 v[116:119], v[146:149], v[200:203], v[116:119]
	v_mfma_f32_16x16x32_bf16 v[112:115], v[166:169], v[200:203], v[112:115]
	v_mfma_f32_16x16x32_bf16 v[108:111], v[146:149], v[208:211], v[108:111]
	v_mfma_f32_16x16x32_bf16 v[104:107], v[166:169], v[208:211], v[104:107]
	v_mfma_f32_16x16x32_bf16 v[100:103], v[146:149], v[216:219], v[100:103]
	v_mfma_f32_16x16x32_bf16 v[96:99], v[166:169], v[216:219], v[96:99]
	v_mfma_f32_16x16x32_bf16 v[124:127], v[162:165], v[196:199], v[124:127]
	v_mfma_f32_16x16x32_bf16 v[120:123], v[170:173], v[196:199], v[120:123]
	v_mfma_f32_16x16x32_bf16 v[116:119], v[162:165], v[204:207], v[116:119]
	v_mfma_f32_16x16x32_bf16 v[112:115], v[170:173], v[204:207], v[112:115]
	v_mfma_f32_16x16x32_bf16 v[108:111], v[162:165], v[212:215], v[108:111]
	v_mfma_f32_16x16x32_bf16 v[104:107], v[170:173], v[212:215], v[104:107]
	v_mfma_f32_16x16x32_bf16 v[100:103], v[162:165], v[220:223], v[100:103]
	v_mfma_f32_16x16x32_bf16 v[96:99], v[170:173], v[220:223], v[96:99]
	s_setprio 0
	s_setprio 1
	v_mfma_f32_16x16x32_bf16 v[68:71], v[176:179], v[192:195], v[68:71]
	v_mfma_f32_16x16x32_bf16 v[64:67], v[184:187], v[192:195], v[64:67]
	v_mfma_f32_16x16x32_bf16 v[56:59], v[176:179], v[200:203], v[56:59]
	v_mfma_f32_16x16x32_bf16 v[48:51], v[184:187], v[200:203], v[48:51]
	v_mfma_f32_16x16x32_bf16 v[44:47], v[176:179], v[208:211], v[44:47]
	v_mfma_f32_16x16x32_bf16 v[40:43], v[184:187], v[208:211], v[40:43]
	v_mfma_f32_16x16x32_bf16 v[36:39], v[176:179], v[216:219], v[36:39]
	v_mfma_f32_16x16x32_bf16 v[32:35], v[184:187], v[216:219], v[32:35]
	v_mfma_f32_16x16x32_bf16 v[68:71], v[180:183], v[196:199], v[68:71]
	v_mfma_f32_16x16x32_bf16 v[64:67], v[188:191], v[196:199], v[64:67]
	v_mfma_f32_16x16x32_bf16 v[56:59], v[180:183], v[204:207], v[56:59]
	v_mfma_f32_16x16x32_bf16 v[48:51], v[188:191], v[204:207], v[48:51]
	v_mfma_f32_16x16x32_bf16 v[44:47], v[180:183], v[212:215], v[44:47]
	v_mfma_f32_16x16x32_bf16 v[40:43], v[188:191], v[212:215], v[40:43]
	v_mfma_f32_16x16x32_bf16 v[36:39], v[180:183], v[220:223], v[36:39]
	v_mfma_f32_16x16x32_bf16 v[32:35], v[188:191], v[220:223], v[32:35]
	s_setprio 0
	s_barrier
; #define PG8_STAGE(bufoff, gbase, voff) do { _Pragma("unroll") for (int _i = 0; _i < 2; ++_i) \
;         __builtin_amdgcn_global_load_lds((const unsigned*)((const char*)(gbase) + (voff)[_i]), (PG8_LAS unsigned*)(lds + (bufoff) + ldsw + _i * 8192), 16, 0, 0); } while (0)
; #define PG8_LDA(dst, b, h) do { _Pragma("unroll") for (int m = 0; m < 4; ++m) _Pragma("unroll") for (int k = 0; k < 2; ++k) dst[m][k] = *(const PG8_LAS bf16x8*)(lds + PG8_SA(b, h) + aoff + m * 2048 + k * 1024); } while (0)
; #define PG8_MMA(ai, bj, At, Bt) do { __builtin_amdgcn_s_setprio(1); _Pragma("unroll") for (int m = 0; m < 4; ++m) _Pragma("unroll") for (int n = 0; n < 2; ++n) _Pragma("unroll") for (int k = 0; k < 2; ++k) \
;         acc[ai][bj][m][n] = __builtin_amdgcn_mfma_f32_16x16x32_bf16(Bt[n][k], At[m][k], acc[ai][bj][m][n], 0, 0, 0); __builtin_amdgcn_s_setprio(0); } while (0)
; #define PG8_WAIT_V(n) asm volatile("s_waitcnt vmcnt(" #n ")" ::: "memory")
; #define PG8_WAIT_L(n) asm volatile("s_waitcnt lgkmcnt(" #n ")" ::: "memory")
; #define PG8_BAR __builtin_amdgcn_s_barrier()
; #define PG8_SCHED __builtin_amdgcn_sched_barrier(0)
; template <class Epi, class Sched, bool ALIGN_EPI = false, bool SP2 = false>
; __device__ __forceinline__ void gemm_phase(PG8_LAS unsigned char* lds, const Gemm g, const Sched& S, const Epi& E) {
;     ...
;             PG8_LDA(At, 1, 1); PG8_STAGE(PG8_SB(1, 0), b3, voffB); PG8_STAGE(PG8_SB(1, 1), b3 + hstepB, voffB); PG8_STAGE(PG8_SA(1, 0), a3, voffA);
;             PG8_WAIT_V(8); PG8_WAIT_L(0); PG8_BAR; PG8_MMA(1, 0, At, B0); PG8_MMA(1, 1, At, B1); PG8_BAR; PG8_SCHED;
	s_add_i32 s75, s75, s27
	v_lshl_add_u64 v[224:225], v[224:225], 0, s[8:9]
	s_mov_b32 m0, s75
	ds_read_b128 v[192:195], v161 offset:49152
	ds_read_b128 v[196:199], v161 offset:50176
	ds_read_b128 v[200:203], v161 offset:51200
	ds_read_b128 v[204:207], v161 offset:52224
	ds_read_b128 v[208:211], v161 offset:53248
	ds_read_b128 v[212:215], v161 offset:54272
	ds_read_b128 v[216:219], v161 offset:55296
	ds_read_b128 v[220:223], v161 offset:56320
	global_load_lds_dwordx4 v[224:225], off nt
	s_add_i32 m0, s75, 0x2000
	s_add_u32 s66, s66, 0x40080
	v_lshl_add_u64 v[224:225], v[226:227], 0, s[8:9]
	s_addc_u32 s67, s67, 0
	s_add_i32 s33, s33, s27
	global_load_lds_dwordx4 v[224:225], off nt
	v_lshl_add_u64 v[224:225], s[66:67], 0, v[132:133]
	s_mov_b32 m0, s33
	s_nop 0
	global_load_lds_dwordx4 v[224:225], off nt
	v_lshl_add_u64 v[224:225], s[66:67], 0, v[128:129]
	s_add_i32 m0, s33, 0x2000
	s_nop 0
	global_load_lds_dwordx4 v[224:225], off nt
	v_lshl_add_u64 v[224:225], v[228:229], 0, s[8:9]
	s_mov_b32 m0, s91
	s_nop 0
	global_load_lds_dwordx4 v[224:225], off
	v_lshl_add_u64 v[224:225], v[230:231], 0, s[8:9]
	s_mov_b32 m0, s92
	s_nop 0
	global_load_lds_dwordx4 v[224:225], off
	s_waitcnt vmcnt(8)
	s_waitcnt lgkmcnt(0)
	s_barrier
	s_setprio 1
	s_waitcnt lgkmcnt(0)
	v_mfma_f32_16x16x32_bf16 v[92:95], v[146:149], v[192:195], v[92:95]
	v_mfma_f32_16x16x32_bf16 v[88:91], v[166:169], v[192:195], v[88:91]
	v_mfma_f32_16x16x32_bf16 v[84:87], v[146:149], v[200:203], v[84:87]
	v_mfma_f32_16x16x32_bf16 v[80:83], v[166:169], v[200:203], v[80:83]
	v_mfma_f32_16x16x32_bf16 v[76:79], v[146:149], v[208:211], v[76:79]
	v_mfma_f32_16x16x32_bf16 v[72:75], v[166:169], v[208:211], v[72:75]
	v_mfma_f32_16x16x32_bf16 v[60:63], v[146:149], v[216:219], v[60:63]
	v_mfma_f32_16x16x32_bf16 v[52:55], v[166:169], v[216:219], v[52:55]
	v_mfma_f32_16x16x32_bf16 v[92:95], v[162:165], v[196:199], v[92:95]
	v_mfma_f32_16x16x32_bf16 v[88:91], v[170:173], v[196:199], v[88:91]
	v_mfma_f32_16x16x32_bf16 v[84:87], v[162:165], v[204:207], v[84:87]
	v_mfma_f32_16x16x32_bf16 v[80:83], v[170:173], v[204:207], v[80:83]
	v_mfma_f32_16x16x32_bf16 v[76:79], v[162:165], v[212:215], v[76:79]
	v_mfma_f32_16x16x32_bf16 v[72:75], v[170:173], v[212:215], v[72:75]
	v_mfma_f32_16x16x32_bf16 v[60:63], v[162:165], v[220:223], v[60:63]
	v_mfma_f32_16x16x32_bf16 v[52:55], v[170:173], v[220:223], v[52:55]
	s_setprio 0
	s_setprio 1
	v_mfma_f32_16x16x32_bf16 v[28:31], v[176:179], v[192:195], v[28:31]
	v_mfma_f32_16x16x32_bf16 v[24:27], v[184:187], v[192:195], v[24:27]
	v_mfma_f32_16x16x32_bf16 v[20:23], v[176:179], v[200:203], v[20:23]
	v_mfma_f32_16x16x32_bf16 v[16:19], v[184:187], v[200:203], v[16:19]
	v_mfma_f32_16x16x32_bf16 v[12:15], v[176:179], v[208:211], v[12:15]
	v_mfma_f32_16x16x32_bf16 v[8:11], v[184:187], v[208:211], v[8:11]
	v_mfma_f32_16x16x32_bf16 v[4:7], v[176:179], v[216:219], v[4:7]
	v_mfma_f32_16x16x32_bf16 v[0:3], v[184:187], v[216:219], v[0:3]
	v_mfma_f32_16x16x32_bf16 v[28:31], v[180:183], v[196:199], v[28:31]
	v_mfma_f32_16x16x32_bf16 v[24:27], v[188:191], v[196:199], v[24:27]
	v_mfma_f32_16x16x32_bf16 v[20:23], v[180:183], v[204:207], v[20:23]
	v_mfma_f32_16x16x32_bf16 v[16:19], v[188:191], v[204:207], v[16:19]
	v_mfma_f32_16x16x32_bf16 v[12:15], v[180:183], v[212:215], v[12:15]
	v_mfma_f32_16x16x32_bf16 v[8:11], v[188:191], v[212:215], v[8:11]
	v_mfma_f32_16x16x32_bf16 v[4:7], v[180:183], v[220:223], v[4:7]
	v_mfma_f32_16x16x32_bf16 v[0:3], v[188:191], v[220:223], v[0:3]
	s_setprio 0
	s_barrier
	s_add_i32 s74, s74, 2
	s_add_u32 s60, s60, 0x100
	s_addc_u32 s61, s61, 0
	s_add_u32 s80, s80, 0x100
	s_addc_u32 s81, s81, 0
	s_cmp_gt_u32 s74, 13
	s_branch .LBB0_197
